# stack17 + packed-f32 softmax (v_pk_fma_f32/v_pk_add_f32) in attention fast path
# speedup vs baseline: 1.0247x; 1.0247x over previous
.Li0_sm:
	ds_read_b64_tr_b16 v[188:189], v158 offset:0x400
	ds_read_b64_tr_b16 v[190:191], v158 offset:0xc00
	ds_read_b64_tr_b16 v[192:193], v158 offset:0x600
	ds_read_b64_tr_b16 v[194:195], v158 offset:0xe00
	s_waitcnt lgkmcnt(6)
	v_mfma_f32_32x32x16_bf16 v[48:63], v[176:179], v[180:183], v[48:63]
	ds_read_b64_tr_b16 v[180:181], v158 offset:0x1000
	ds_read_b64_tr_b16 v[182:183], v158 offset:0x1800
	s_mov_b32 s54, 0x3e0293ee
	s_mov_b32 s55, 0x3e0293ee
	v_mul_f32_e32 v116, 0xbe0293ee, v166
	v_max_f32_e32 v112, v65, v65
	v_max_f32_e32 v113, v64, v64
	v_mul_f32_e32 v117, 0xbe0293ee, v166
	s_waitcnt lgkmcnt(6)
	v_mfma_f32_32x32x16_bf16 v[32:47], v[176:179], v[184:187], v[32:47]
	ds_read_b64_tr_b16 v[184:185], v158 offset:0x1200
	ds_read_b64_tr_b16 v[186:187], v158 offset:0x1a00
	v_max_f32_e32 v112, v113, v112
	v_pk_fma_f32 v[64:65], v[64:65], s[54:55], v[116:117]
	v_max3_f32 v112, v112, v66, v67
	v_exp_f32_e32 v64, v64
	s_waitcnt lgkmcnt(6)
	v_mfma_f32_32x32x16_bf16 v[16:31], v[176:179], v[188:191], v[16:31]
	ds_read_b64_tr_b16 v[188:189], v158 offset:0x1400
	ds_read_b64_tr_b16 v[190:191], v158 offset:0x1c00
	v_exp_f32_e32 v65, v65
	v_pk_fma_f32 v[66:67], v[66:67], s[54:55], v[116:117]
	v_max3_f32 v112, v112, v68, v69
	v_exp_f32_e32 v66, v66
	s_waitcnt lgkmcnt(6)
	v_mfma_f32_32x32x16_bf16 v[0:15], v[176:179], v[192:195], v[0:15]
	ds_read_b64_tr_b16 v[192:193], v158 offset:0x1600
	ds_read_b64_tr_b16 v[194:195], v158 offset:0x1e00
	v_exp_f32_e32 v67, v67
	v_pk_fma_f32 v[68:69], v[68:69], s[54:55], v[116:117]
	v_max3_f32 v112, v112, v70, v71
	v_exp_f32_e32 v68, v68
	s_waitcnt lgkmcnt(6)
	v_mfma_f32_32x32x16_bf16 v[48:63], v[124:127], v[180:183], v[48:63]
	ds_read_b64_tr_b16 v[180:181], v158 offset:0x2000
	ds_read_b64_tr_b16 v[182:183], v158 offset:0x2800
	v_exp_f32_e32 v69, v69
	v_pk_add_f32 v[118:119], v[64:65], v[66:67]
	v_pk_fma_f32 v[70:71], v[70:71], s[54:55], v[116:117]
	v_max3_f32 v112, v112, v72, v73
	s_waitcnt lgkmcnt(6)
	v_mfma_f32_32x32x16_bf16 v[32:47], v[124:127], v[184:187], v[32:47]
	ds_read_b64_tr_b16 v[184:185], v158 offset:0x2200
	ds_read_b64_tr_b16 v[186:187], v158 offset:0x2a00
	v_exp_f32_e32 v70, v70
	v_exp_f32_e32 v71, v71
	v_pk_add_f32 v[118:119], v[118:119], v[68:69]
	v_pk_fma_f32 v[72:73], v[72:73], s[54:55], v[116:117]
	s_waitcnt lgkmcnt(6)
	v_mfma_f32_32x32x16_bf16 v[16:31], v[124:127], v[188:191], v[16:31]
	ds_read_b64_tr_b16 v[188:189], v158 offset:0x2400
	ds_read_b64_tr_b16 v[190:191], v158 offset:0x2c00
	v_max3_f32 v112, v112, v74, v75
	v_exp_f32_e32 v72, v72
	v_exp_f32_e32 v73, v73
	v_pk_add_f32 v[118:119], v[118:119], v[70:71]
	s_waitcnt lgkmcnt(6)
	v_mfma_f32_32x32x16_bf16 v[0:15], v[124:127], v[192:195], v[0:15]
	ds_read_b64_tr_b16 v[192:193], v158 offset:0x2600
	ds_read_b64_tr_b16 v[194:195], v158 offset:0x2e00
	v_pk_fma_f32 v[74:75], v[74:75], s[54:55], v[116:117]
	v_max3_f32 v112, v112, v76, v77
	v_exp_f32_e32 v74, v74
	v_exp_f32_e32 v75, v75
	s_waitcnt lgkmcnt(6)
	v_mfma_f32_32x32x16_bf16 v[48:63], v[172:175], v[180:183], v[48:63]
	ds_read_b64_tr_b16 v[180:181], v158 offset:0x3000
	ds_read_b64_tr_b16 v[182:183], v158 offset:0x3800
	v_pk_add_f32 v[118:119], v[118:119], v[72:73]
	v_pk_fma_f32 v[76:77], v[76:77], s[54:55], v[116:117]
	v_max3_f32 v112, v112, v78, v79
	v_exp_f32_e32 v76, v76
	s_waitcnt lgkmcnt(6)
	v_mfma_f32_32x32x16_bf16 v[32:47], v[172:175], v[184:187], v[32:47]
	ds_read_b64_tr_b16 v[184:185], v158 offset:0x3200
	ds_read_b64_tr_b16 v[186:187], v158 offset:0x3a00
	v_exp_f32_e32 v77, v77
	v_pk_add_f32 v[118:119], v[118:119], v[74:75]
	v_pk_fma_f32 v[78:79], v[78:79], s[54:55], v[116:117]
	v_exp_f32_e32 v78, v78
	s_waitcnt lgkmcnt(6)
	v_mfma_f32_32x32x16_bf16 v[16:31], v[172:175], v[188:191], v[16:31]
	ds_read_b64_tr_b16 v[188:189], v158 offset:0x3400
	ds_read_b64_tr_b16 v[190:191], v158 offset:0x3c00
	v_exp_f32_e32 v79, v79
	v_pk_add_f32 v[118:119], v[118:119], v[76:77]
	v_mov_b32_e32 v113, v112
	v_pk_add_f32 v[118:119], v[118:119], v[78:79]
	s_waitcnt lgkmcnt(6)
	v_mfma_f32_32x32x16_bf16 v[0:15], v[172:175], v[192:195], v[0:15]
	ds_read_b64_tr_b16 v[192:193], v158 offset:0x3600
	ds_read_b64_tr_b16 v[194:195], v158 offset:0x3e00
	s_nop 0
	v_permlane32_swap_b32_e32 v112, v113
	v_add_f32_e32 v120, v118, v119
	v_max_f32_e32 v113, v113, v113
	v_max_f32_e32 v112, v112, v112
	v_max_f32_e32 v164, v112, v113
	v_mov_b32_e32 v121, v120
	s_waitcnt lgkmcnt(6)
	v_mfma_f32_32x32x16_bf16 v[48:63], v[168:171], v[180:183], v[48:63]
	v_cvt_pk_bf16_f32 v112, v64, v65
	v_cvt_pk_bf16_f32 v113, v66, v67
	v_cvt_pk_bf16_f32 v114, v68, v69
	v_cvt_pk_bf16_f32 v115, v70, v71
	v_cvt_pk_bf16_f32 v116, v72, v73
	v_cvt_pk_bf16_f32 v117, v74, v75
	s_waitcnt lgkmcnt(4)
	v_mfma_f32_32x32x16_bf16 v[32:47], v[168:171], v[184:187], v[32:47]
	v_cvt_pk_bf16_f32 v118, v76, v77
	v_cvt_pk_bf16_f32 v119, v78, v79
	s_nop 1
	v_permlane32_swap_b32_e32 v120, v121
	v_permlane32_swap_b32_e32 v112, v114
	v_permlane32_swap_b32_e32 v113, v115
	s_waitcnt lgkmcnt(2)
	v_mfma_f32_32x32x16_bf16 v[16:31], v[168:171], v[188:191], v[16:31]
	v_permlane32_swap_b32_e32 v116, v118
	v_permlane32_swap_b32_e32 v117, v119
	ds_write_b128 v157, v[112:115] offset:4096
	ds_write_b128 v157, v[116:119] offset:5120
	v_add_f32_e32 v120, v120, v121
	v_add_f32_e32 v155, v155, v120
	s_waitcnt lgkmcnt(2)
	v_mfma_f32_32x32x16_bf16 v[0:15], v[168:171], v[192:195], v[0:15]
	s_and_saveexec_b64 s[52:53], s[4:5]
	ds_write_b32 v160, v164 offset:8448
	s_or_b64 exec, exec, s[52:53]
	s_waitcnt vmcnt(0)
	s_waitcnt vmcnt(0) lgkmcnt(0)
	s_barrier
	s_branch .LBB0_748

.Li1_sm:
	ds_read_b64_tr_b16 v[188:189], v158 offset:0x8400
	ds_read_b64_tr_b16 v[190:191], v158 offset:0x8c00
	ds_read_b64_tr_b16 v[192:193], v158 offset:0x8600
	ds_read_b64_tr_b16 v[194:195], v158 offset:0x8e00
	s_waitcnt lgkmcnt(6)
	v_mfma_f32_32x32x16_bf16 v[48:63], v[176:179], v[180:183], v[48:63]
	ds_read_b64_tr_b16 v[180:181], v158 offset:0x9000
	ds_read_b64_tr_b16 v[182:183], v158 offset:0x9800
	s_mov_b32 s56, 0x3e0293ee
	s_mov_b32 s57, 0x3e0293ee
	v_mul_f32_e32 v116, 0xbe0293ee, v165
	v_max_f32_e32 v112, v65, v65
	v_max_f32_e32 v113, v64, v64
	v_mul_f32_e32 v117, 0xbe0293ee, v165
	s_waitcnt lgkmcnt(6)
	v_mfma_f32_32x32x16_bf16 v[32:47], v[176:179], v[184:187], v[32:47]
	ds_read_b64_tr_b16 v[184:185], v158 offset:0x9200
	ds_read_b64_tr_b16 v[186:187], v158 offset:0x9a00
	v_max_f32_e32 v112, v113, v112
	v_pk_fma_f32 v[64:65], v[64:65], s[56:57], v[116:117]
	v_max3_f32 v112, v112, v66, v67
	v_exp_f32_e32 v64, v64
	s_waitcnt lgkmcnt(6)
	v_mfma_f32_32x32x16_bf16 v[16:31], v[176:179], v[188:191], v[16:31]
	ds_read_b64_tr_b16 v[188:189], v158 offset:0x9400
	ds_read_b64_tr_b16 v[190:191], v158 offset:0x9c00
	v_exp_f32_e32 v65, v65
	v_pk_fma_f32 v[66:67], v[66:67], s[56:57], v[116:117]
	v_max3_f32 v112, v112, v68, v69
	v_exp_f32_e32 v66, v66
	s_waitcnt lgkmcnt(6)
	v_mfma_f32_32x32x16_bf16 v[0:15], v[176:179], v[192:195], v[0:15]
	ds_read_b64_tr_b16 v[192:193], v158 offset:0x9600
	ds_read_b64_tr_b16 v[194:195], v158 offset:0x9e00
	v_exp_f32_e32 v67, v67
	v_pk_fma_f32 v[68:69], v[68:69], s[56:57], v[116:117]
	v_max3_f32 v112, v112, v70, v71
	v_exp_f32_e32 v68, v68
	s_waitcnt lgkmcnt(6)
	v_mfma_f32_32x32x16_bf16 v[48:63], v[168:171], v[180:183], v[48:63]
	ds_read_b64_tr_b16 v[180:181], v158 offset:0xa000
	ds_read_b64_tr_b16 v[182:183], v158 offset:0xa800
	v_exp_f32_e32 v69, v69
	v_pk_add_f32 v[118:119], v[64:65], v[66:67]
	v_pk_fma_f32 v[70:71], v[70:71], s[56:57], v[116:117]
	v_max3_f32 v112, v112, v72, v73
	s_waitcnt lgkmcnt(6)
	v_mfma_f32_32x32x16_bf16 v[32:47], v[168:171], v[184:187], v[32:47]
	ds_read_b64_tr_b16 v[184:185], v158 offset:0xa200
	ds_read_b64_tr_b16 v[186:187], v158 offset:0xaa00
	v_exp_f32_e32 v70, v70
	v_exp_f32_e32 v71, v71
	v_pk_add_f32 v[118:119], v[118:119], v[68:69]
	v_pk_fma_f32 v[72:73], v[72:73], s[56:57], v[116:117]
	s_waitcnt lgkmcnt(6)
	v_mfma_f32_32x32x16_bf16 v[16:31], v[168:171], v[188:191], v[16:31]
	ds_read_b64_tr_b16 v[188:189], v158 offset:0xa400
	ds_read_b64_tr_b16 v[190:191], v158 offset:0xac00
	v_max3_f32 v112, v112, v74, v75
	v_exp_f32_e32 v72, v72
	v_exp_f32_e32 v73, v73
	v_pk_add_f32 v[118:119], v[118:119], v[70:71]
	s_waitcnt lgkmcnt(6)
	v_mfma_f32_32x32x16_bf16 v[0:15], v[168:171], v[192:195], v[0:15]
	ds_read_b64_tr_b16 v[192:193], v158 offset:0xa600
	ds_read_b64_tr_b16 v[194:195], v158 offset:0xae00
	v_pk_fma_f32 v[74:75], v[74:75], s[56:57], v[116:117]
	v_max3_f32 v112, v112, v76, v77
	v_exp_f32_e32 v74, v74
	v_exp_f32_e32 v75, v75
	s_waitcnt lgkmcnt(6)
	v_mfma_f32_32x32x16_bf16 v[48:63], v[172:175], v[180:183], v[48:63]
	ds_read_b64_tr_b16 v[180:181], v158 offset:0xb000
	ds_read_b64_tr_b16 v[182:183], v158 offset:0xb800
	v_pk_add_f32 v[118:119], v[118:119], v[72:73]
	v_pk_fma_f32 v[76:77], v[76:77], s[56:57], v[116:117]
	v_max3_f32 v112, v112, v78, v79
	v_exp_f32_e32 v76, v76
	s_waitcnt lgkmcnt(6)
	v_mfma_f32_32x32x16_bf16 v[32:47], v[172:175], v[184:187], v[32:47]
	ds_read_b64_tr_b16 v[184:185], v158 offset:0xb200
	ds_read_b64_tr_b16 v[186:187], v158 offset:0xba00
	v_exp_f32_e32 v77, v77
	v_pk_add_f32 v[118:119], v[118:119], v[74:75]
	v_pk_fma_f32 v[78:79], v[78:79], s[56:57], v[116:117]
	v_exp_f32_e32 v78, v78
	s_waitcnt lgkmcnt(6)
	v_mfma_f32_32x32x16_bf16 v[16:31], v[172:175], v[188:191], v[16:31]
	ds_read_b64_tr_b16 v[188:189], v158 offset:0xb400
	ds_read_b64_tr_b16 v[190:191], v158 offset:0xbc00
	v_exp_f32_e32 v79, v79
	v_pk_add_f32 v[118:119], v[118:119], v[76:77]
	v_mov_b32_e32 v113, v112
	v_pk_add_f32 v[118:119], v[118:119], v[78:79]
	s_waitcnt lgkmcnt(6)
	v_mfma_f32_32x32x16_bf16 v[0:15], v[172:175], v[192:195], v[0:15]
	ds_read_b64_tr_b16 v[192:193], v158 offset:0xb600
	ds_read_b64_tr_b16 v[194:195], v158 offset:0xbe00
	s_nop 0
	v_permlane32_swap_b32_e32 v112, v113
	v_add_f32_e32 v120, v118, v119
	v_max_f32_e32 v113, v113, v113
	v_max_f32_e32 v112, v112, v112
	v_max_f32_e32 v164, v112, v113
	v_mov_b32_e32 v121, v120
	s_waitcnt lgkmcnt(6)
	v_mfma_f32_32x32x16_bf16 v[48:63], v[124:127], v[180:183], v[48:63]
	v_cvt_pk_bf16_f32 v112, v64, v65
	v_cvt_pk_bf16_f32 v113, v66, v67
	v_cvt_pk_bf16_f32 v114, v68, v69
	v_cvt_pk_bf16_f32 v115, v70, v71
	v_cvt_pk_bf16_f32 v116, v72, v73
	v_cvt_pk_bf16_f32 v117, v74, v75
	s_waitcnt lgkmcnt(4)
	v_mfma_f32_32x32x16_bf16 v[32:47], v[124:127], v[184:187], v[32:47]
	v_cvt_pk_bf16_f32 v118, v76, v77
	v_cvt_pk_bf16_f32 v119, v78, v79
	s_nop 1
	v_permlane32_swap_b32_e32 v120, v121
	v_permlane32_swap_b32_e32 v112, v114
	v_permlane32_swap_b32_e32 v113, v115
	s_waitcnt lgkmcnt(2)
	v_mfma_f32_32x32x16_bf16 v[16:31], v[124:127], v[188:191], v[16:31]
	v_permlane32_swap_b32_e32 v116, v118
	v_permlane32_swap_b32_e32 v117, v119
	ds_write_b128 v157, v[112:115]
	ds_write_b128 v157, v[116:119] offset:1024
	v_add_f32_e32 v120, v120, v121
	v_add_f32_e32 v155, v155, v120
	s_waitcnt lgkmcnt(2)
	v_mfma_f32_32x32x16_bf16 v[0:15], v[124:127], v[192:195], v[0:15]
	s_and_saveexec_b64 s[54:55], s[4:5]
	ds_write_b32 v160, v164 offset:8192
	s_or_b64 exec, exec, s[54:55]
	s_waitcnt vmcnt(0)
	s_waitcnt vmcnt(0) lgkmcnt(0)
	s_barrier
	s_branch .LBB0_733
